# grid barrier: non-leader workgroups poll the cross-XCD release generation directly (one hop less on release), on top of k-inner MFMA order
# speedup vs baseline: 1.0116x; 1.0116x over previous
.LBB0_73:
	s_or_b64 exec, exec, s[10:11]
	v_cvt_f32_u32_e32 v4, v2
	s_waitcnt vmcnt(0)
	v_readfirstlane_b32 s3, v3
	v_sub_u32_e32 v3, 0, v2
	v_rcp_iflag_f32_e32 v4, v4
	v_add_u32_e32 v5, s3, v1
	v_mul_f32_e32 v4, 0x4f7ffffe, v4
	v_cvt_u32_f32_e32 v4, v4
	v_mul_lo_u32 v1, v3, v4
	v_mul_hi_u32 v1, v4, v1
	v_add_u32_e32 v1, v4, v1
	v_mul_hi_u32 v1, v5, v1
	v_mul_lo_u32 v3, v1, v2
	v_sub_u32_e32 v3, v5, v3
	v_add_u32_e32 v4, 1, v1
	v_cmp_ge_u32_e32 vcc, v3, v2
	s_nop 1
	v_cndmask_b32_e32 v1, v1, v4, vcc
	v_sub_u32_e32 v4, v3, v2
	v_cndmask_b32_e32 v3, v3, v4, vcc
	v_add_u32_e32 v4, 1, v1
	v_cmp_ge_u32_e32 vcc, v3, v2
	v_add_u32_e32 v3, 1, v5
	s_nop 0
	v_cndmask_b32_e32 v1, v1, v4, vcc
	v_mul_lo_u32 v4, v2, v1
	v_add_u32_e32 v2, v4, v2
	v_cmp_ne_u32_e32 vcc, v3, v2
	s_and_saveexec_b64 s[8:9], vcc
	s_xor_b64 s[8:9], exec, s[8:9]
	s_cbranch_execz .LBB0_87
	s_waitcnt lgkmcnt(0)
	v_readlane_b32 s14, v253, 6
	v_readlane_b32 s15, v253, 7
	v_mov_b32_e32 v0, 0
	s_add_u32 s14, s14, 0x7500
	s_addc_u32 s15, s15, 0
	s_nop 4
	global_load_dword v0, v0, s[14:15] sc1
	s_waitcnt vmcnt(0)
	v_cmp_eq_u32_e32 vcc, v0, v1
	s_and_saveexec_b64 s[10:11], vcc
	s_cbranch_execz .LBB0_86
	v_readlane_b32 s16, v253, 4
	v_readlane_b32 s18, v253, 6
	v_readlane_b32 s17, v253, 5
	v_readlane_b32 s19, v253, 7
	s_add_u32 s12, s18, 0x4200
	s_addc_u32 s13, s19, 0
	s_mov_b32 s3, 1
	s_mov_b64 s[16:17], 0
	v_mov_b32_e32 v0, 0
	s_branch .LBB0_77

.LBB0_474:
	s_or_b64 exec, exec, s[8:9]
	v_cvt_f32_u32_e32 v4, v2
	s_waitcnt vmcnt(0)
	v_readfirstlane_b32 s3, v3
	v_sub_u32_e32 v3, 0, v2
	v_rcp_iflag_f32_e32 v4, v4
	v_add_u32_e32 v5, s3, v1
	v_mul_f32_e32 v4, 0x4f7ffffe, v4
	v_cvt_u32_f32_e32 v4, v4
	v_mul_lo_u32 v1, v3, v4
	v_mul_hi_u32 v1, v4, v1
	v_add_u32_e32 v1, v4, v1
	v_mul_hi_u32 v1, v5, v1
	v_mul_lo_u32 v3, v1, v2
	v_sub_u32_e32 v3, v5, v3
	v_add_u32_e32 v4, 1, v1
	v_cmp_ge_u32_e32 vcc, v3, v2
	s_nop 1
	v_cndmask_b32_e32 v1, v1, v4, vcc
	v_sub_u32_e32 v4, v3, v2
	v_cndmask_b32_e32 v3, v3, v4, vcc
	v_add_u32_e32 v4, 1, v1
	v_cmp_ge_u32_e32 vcc, v3, v2
	v_add_u32_e32 v3, 1, v5
	s_nop 0
	v_cndmask_b32_e32 v1, v1, v4, vcc
	v_mul_lo_u32 v4, v2, v1
	v_add_u32_e32 v2, v4, v2
	v_cmp_ne_u32_e32 vcc, v3, v2
	s_and_saveexec_b64 s[6:7], vcc
	s_xor_b64 s[6:7], exec, s[6:7]
	s_cbranch_execz .LBB0_488
	s_waitcnt lgkmcnt(0)
	v_readlane_b32 s12, v253, 6
	v_readlane_b32 s13, v253, 7
	v_mov_b32_e32 v0, 0
	s_add_u32 s12, s12, 0x7500
	s_addc_u32 s13, s13, 0
	s_nop 4
	global_load_dword v0, v0, s[12:13] sc1
	s_waitcnt vmcnt(0)
	v_cmp_eq_u32_e32 vcc, v0, v1
	s_and_saveexec_b64 s[8:9], vcc
	s_cbranch_execz .LBB0_487
	v_readlane_b32 s16, v253, 4
	v_readlane_b32 s18, v253, 6
	v_readlane_b32 s19, v253, 7
	s_add_u32 s10, s18, 0x4200
	v_readlane_b32 s17, v253, 5
	s_addc_u32 s11, s19, 0
	s_mov_b32 s3, 1
	s_mov_b64 s[14:15], 0
	v_mov_b32_e32 v0, 0
	s_branch .LBB0_478

.LBB0_561:
	s_or_b64 exec, exec, s[10:11]
	v_cvt_f32_u32_e32 v4, v2
	s_waitcnt vmcnt(0)
	v_readfirstlane_b32 s10, v3
	v_sub_u32_e32 v3, 0, v2
	v_rcp_iflag_f32_e32 v4, v4
	v_add_u32_e32 v5, s10, v1
	v_mul_f32_e32 v4, 0x4f7ffffe, v4
	v_cvt_u32_f32_e32 v4, v4
	v_mul_lo_u32 v1, v3, v4
	v_mul_hi_u32 v1, v4, v1
	v_add_u32_e32 v1, v4, v1
	v_mul_hi_u32 v1, v5, v1
	v_mul_lo_u32 v3, v1, v2
	v_sub_u32_e32 v3, v5, v3
	v_add_u32_e32 v4, 1, v1
	v_cmp_ge_u32_e32 vcc, v3, v2
	s_nop 1
	v_cndmask_b32_e32 v1, v1, v4, vcc
	v_sub_u32_e32 v4, v3, v2
	v_cndmask_b32_e32 v3, v3, v4, vcc
	v_add_u32_e32 v4, 1, v1
	v_cmp_ge_u32_e32 vcc, v3, v2
	v_add_u32_e32 v3, 1, v5
	s_nop 0
	v_cndmask_b32_e32 v1, v1, v4, vcc
	v_mul_lo_u32 v4, v2, v1
	v_add_u32_e32 v2, v4, v2
	v_cmp_ne_u32_e32 vcc, v3, v2
	s_and_saveexec_b64 s[10:11], vcc
	s_xor_b64 s[10:11], exec, s[10:11]
	s_cbranch_execz .LBB0_575
	v_readlane_b32 s14, v253, 26
	v_readlane_b32 s15, v253, 27
	s_waitcnt lgkmcnt(0)
	s_nop 3
	global_load_dword v0, v129, s[14:15] sc1
	s_waitcnt vmcnt(0)
	v_cmp_eq_u32_e32 vcc, v0, v1
	s_and_saveexec_b64 s[24:25], vcc
	s_cbranch_execz .LBB0_574
	s_mov_b32 s14, 1
	s_mov_b64 s[36:37], 0
	s_branch .LBB0_565

.LBB0_567:
	v_readlane_b32 s16, v253, 26
	v_readlane_b32 s17, v253, 27
	s_add_i32 s14, s14, 1
	s_mov_b64 s[52:53], -1
	s_nop 2
	global_load_dword v0, v129, s[16:17] sc1
	s_waitcnt vmcnt(0)
	v_cmp_ne_u32_e32 vcc, v0, v1
	s_orn2_b64 s[40:41], vcc, exec
	s_branch .LBB0_564

.LBB0_647:
	s_or_b64 exec, exec, s[10:11]
	v_cvt_f32_u32_e32 v4, v2
	s_waitcnt vmcnt(0)
	v_readfirstlane_b32 s8, v3
	v_sub_u32_e32 v3, 0, v2
	v_rcp_iflag_f32_e32 v4, v4
	v_add_u32_e32 v5, s8, v1
	v_mul_f32_e32 v4, 0x4f7ffffe, v4
	v_cvt_u32_f32_e32 v4, v4
	v_mul_lo_u32 v1, v3, v4
	v_mul_hi_u32 v1, v4, v1
	v_add_u32_e32 v1, v4, v1
	v_mul_hi_u32 v1, v5, v1
	v_mul_lo_u32 v3, v1, v2
	v_sub_u32_e32 v3, v5, v3
	v_add_u32_e32 v4, 1, v1
	v_cmp_ge_u32_e32 vcc, v3, v2
	s_nop 1
	v_cndmask_b32_e32 v1, v1, v4, vcc
	v_sub_u32_e32 v4, v3, v2
	v_cndmask_b32_e32 v3, v3, v4, vcc
	v_add_u32_e32 v4, 1, v1
	v_cmp_ge_u32_e32 vcc, v3, v2
	v_add_u32_e32 v3, 1, v5
	s_nop 0
	v_cndmask_b32_e32 v1, v1, v4, vcc
	v_mul_lo_u32 v4, v2, v1
	v_add_u32_e32 v2, v4, v2
	v_cmp_ne_u32_e32 vcc, v3, v2
	s_and_saveexec_b64 s[10:11], vcc
	s_xor_b64 s[10:11], exec, s[10:11]
	s_cbranch_execz .LBB0_661
	v_readlane_b32 s14, v253, 26
	v_readlane_b32 s15, v253, 27
	s_waitcnt lgkmcnt(0)
	s_nop 3
	global_load_dword v0, v129, s[14:15] sc1
	s_waitcnt vmcnt(0)
	v_cmp_eq_u32_e32 vcc, v0, v1
	s_and_saveexec_b64 s[24:25], vcc
	s_cbranch_execz .LBB0_660
	s_mov_b32 s8, 1
	s_mov_b64 s[36:37], 0
	s_branch .LBB0_651

.LBB0_653:
	v_readlane_b32 s14, v253, 26
	v_readlane_b32 s15, v253, 27
	s_add_i32 s8, s8, 1
	s_mov_b64 s[52:53], -1
	s_nop 2
	global_load_dword v0, v129, s[14:15] sc1
	s_waitcnt vmcnt(0)
	v_cmp_ne_u32_e32 vcc, v0, v1
	s_orn2_b64 s[40:41], vcc, exec
	s_branch .LBB0_650
